# carry phase rewritten by hand: 16-load batches software-pipelined 3 deep instead of 4 serial rounds of 32
# baseline (speedup 1.0000x reference)
; __device__ __forceinline__ void carry_phase(const Args& a, int bx) {
;     int tid_ = threadIdx.x; asm volatile("" : "+v"(tid_));
;     const int gt = bx * NTHR + tid_;
;     if (gt >= NB * 2 * LW) return;
;     const int b = gt >> 10, dir = (gt >> 9) & 1, c = gt & 511;
;     const f32x2* tot = (const f32x2*)(a.ws + WS_TOT); float* car = (float*)(a.ws + WS_CAR);
;     float hc = 0.f;
; #pragma unroll 1
;     for (int j0 = 0; j0 < NCH; j0 += 32) {
;         f32x2 v[32];
; #pragma unroll
;         for (int i = 0; i < 32; ++i) { const int j = j0 + i, cj = dir == 0 ? j : NCH - 1 - j; v[i] = tot[(size_t)((b * NCH + cj) * 2 + dir) * LW + c]; }
; #pragma unroll
;         for (int i = 0; i < 32; ++i) { const int j = j0 + i, cj = dir == 0 ? j : NCH - 1 - j; car[(size_t)((b * NCH + cj) * 2 + dir) * LW + c] = hc; hc = v[i].x * hc + v[i].y; }
;     }
; }
.LBB0_252:
	s_or_b64 exec, exec, s[0:1]
	s_waitcnt lgkmcnt(0)
	v_mov_b32_e32 v2, v226
	v_readlane_b32 s0, v253, 34
	s_barrier
	s_nop 0
	v_add_u32_e32 v0, s0, v2
	s_movk_i32 s0, 0x1000
	v_cmp_gt_i32_e32 vcc, s0, v0
	s_and_saveexec_b64 s[0:1], vcc
	s_xor_b64 s[0:1], exec, s[0:1]
	s_cbranch_execz .LBB0_255
	v_bfe_u32 v3, v0, 9, 1
	v_and_b32_e32 v4, 0x1ff, v2
	v_ashrrev_i32_e32 v0, 2, v0
	s_movk_i32 s29, 0xff00
	v_and_or_b32 v120, v0, s29, v3
	v_readlane_b32 s4, v253, 35
	v_readlane_b32 s5, v253, 36
	v_lshl_add_u32 v5, v120, 9, v4
	v_cmp_eq_u32_e32 vcc, 0, v3
	v_lshlrev_b32_e32 v6, 3, v5
	v_lshlrev_b32_e32 v7, 2, v5
	v_mov_b32_e32 v8, 0xffffe000
	v_mov_b32_e32 v9, 0x2000
	v_cndmask_b32_e32 v8, v8, v9, vcc
	v_mov_b32_e32 v10, 0xfffff000
	v_mov_b32_e32 v11, 0x1000
	v_cndmask_b32_e32 v10, v10, v11, vcc
	v_mov_b32_e32 v12, 0xfe000
	v_cndmask_b32_e64 v12, v12, 0, vcc
	v_add_u32_e32 v6, v6, v12
	v_mov_b32_e32 v12, 0x7f000
	v_cndmask_b32_e64 v12, v12, 0, vcc
	v_add_u32_e32 v7, v7, v12
	v_mov_b32_e32 v13, 0
	global_load_dwordx2 v[14:15], v6, s[74:75]
	v_add_u32_e32 v6, v6, v8
	global_load_dwordx2 v[16:17], v6, s[74:75]
	v_add_u32_e32 v6, v6, v8
	global_load_dwordx2 v[18:19], v6, s[74:75]
	v_add_u32_e32 v6, v6, v8
	global_load_dwordx2 v[20:21], v6, s[74:75]
	v_add_u32_e32 v6, v6, v8
	global_load_dwordx2 v[22:23], v6, s[74:75]
	v_add_u32_e32 v6, v6, v8
	global_load_dwordx2 v[24:25], v6, s[74:75]
	v_add_u32_e32 v6, v6, v8
	global_load_dwordx2 v[26:27], v6, s[74:75]
	v_add_u32_e32 v6, v6, v8
	global_load_dwordx2 v[28:29], v6, s[74:75]
	v_add_u32_e32 v6, v6, v8
	global_load_dwordx2 v[30:31], v6, s[74:75]
	v_add_u32_e32 v6, v6, v8
	global_load_dwordx2 v[32:33], v6, s[74:75]
	v_add_u32_e32 v6, v6, v8
	global_load_dwordx2 v[34:35], v6, s[74:75]
	v_add_u32_e32 v6, v6, v8
	global_load_dwordx2 v[36:37], v6, s[74:75]
	v_add_u32_e32 v6, v6, v8
	global_load_dwordx2 v[38:39], v6, s[74:75]
	v_add_u32_e32 v6, v6, v8
	global_load_dwordx2 v[40:41], v6, s[74:75]
	v_add_u32_e32 v6, v6, v8
	global_load_dwordx2 v[42:43], v6, s[74:75]
	v_add_u32_e32 v6, v6, v8
	global_load_dwordx2 v[44:45], v6, s[74:75]
	v_add_u32_e32 v6, v6, v8
	global_load_dwordx2 v[46:47], v6, s[74:75]
	v_add_u32_e32 v6, v6, v8
	global_load_dwordx2 v[48:49], v6, s[74:75]
	v_add_u32_e32 v6, v6, v8
	global_load_dwordx2 v[50:51], v6, s[74:75]
	v_add_u32_e32 v6, v6, v8
	global_load_dwordx2 v[52:53], v6, s[74:75]
	v_add_u32_e32 v6, v6, v8
	global_load_dwordx2 v[54:55], v6, s[74:75]
	v_add_u32_e32 v6, v6, v8
	global_load_dwordx2 v[56:57], v6, s[74:75]
	v_add_u32_e32 v6, v6, v8
	global_load_dwordx2 v[58:59], v6, s[74:75]
	v_add_u32_e32 v6, v6, v8
	global_load_dwordx2 v[60:61], v6, s[74:75]
	v_add_u32_e32 v6, v6, v8
	global_load_dwordx2 v[62:63], v6, s[74:75]
	v_add_u32_e32 v6, v6, v8
	global_load_dwordx2 v[64:65], v6, s[74:75]
	v_add_u32_e32 v6, v6, v8
	global_load_dwordx2 v[66:67], v6, s[74:75]
	v_add_u32_e32 v6, v6, v8
	global_load_dwordx2 v[68:69], v6, s[74:75]
	v_add_u32_e32 v6, v6, v8
	global_load_dwordx2 v[70:71], v6, s[74:75]
	v_add_u32_e32 v6, v6, v8
	global_load_dwordx2 v[72:73], v6, s[74:75]
	v_add_u32_e32 v6, v6, v8
	global_load_dwordx2 v[74:75], v6, s[74:75]
	v_add_u32_e32 v6, v6, v8
	global_load_dwordx2 v[76:77], v6, s[74:75]
	v_add_u32_e32 v6, v6, v8
	global_load_dwordx2 v[78:79], v6, s[74:75]
	v_add_u32_e32 v6, v6, v8
	global_load_dwordx2 v[80:81], v6, s[74:75]
	v_add_u32_e32 v6, v6, v8
	global_load_dwordx2 v[82:83], v6, s[74:75]
	v_add_u32_e32 v6, v6, v8
	global_load_dwordx2 v[84:85], v6, s[74:75]
	v_add_u32_e32 v6, v6, v8
	global_load_dwordx2 v[86:87], v6, s[74:75]
	v_add_u32_e32 v6, v6, v8
	global_load_dwordx2 v[88:89], v6, s[74:75]
	v_add_u32_e32 v6, v6, v8
	global_load_dwordx2 v[90:91], v6, s[74:75]
	v_add_u32_e32 v6, v6, v8
	global_load_dwordx2 v[92:93], v6, s[74:75]
	v_add_u32_e32 v6, v6, v8
	global_load_dwordx2 v[94:95], v6, s[74:75]
	v_add_u32_e32 v6, v6, v8
	global_load_dwordx2 v[96:97], v6, s[74:75]
	v_add_u32_e32 v6, v6, v8
	global_load_dwordx2 v[98:99], v6, s[74:75]
	v_add_u32_e32 v6, v6, v8
	global_load_dwordx2 v[100:101], v6, s[74:75]
	v_add_u32_e32 v6, v6, v8
	global_load_dwordx2 v[102:103], v6, s[74:75]
	v_add_u32_e32 v6, v6, v8
	global_load_dwordx2 v[104:105], v6, s[74:75]
	v_add_u32_e32 v6, v6, v8
	global_load_dwordx2 v[106:107], v6, s[74:75]
	v_add_u32_e32 v6, v6, v8
	global_load_dwordx2 v[108:109], v6, s[74:75]
	v_add_u32_e32 v6, v6, v8
	s_waitcnt vmcnt(32)
; __device__ __forceinline__ void carry_phase(const Args& a, int bx) {
;     ...
;     for (int j0 = 0; j0 < NCH; j0 += 32) {
;         f32x2 v[32];
; #pragma unroll
;         for (int i = 0; i < 32; ++i) { const int j = j0 + i, cj = dir == 0 ? j : NCH - 1 - j; v[i] = tot[(size_t)((b * NCH + cj) * 2 + dir) * LW + c]; }
; #pragma unroll
;         for (int i = 0; i < 32; ++i) { const int j = j0 + i, cj = dir == 0 ? j : NCH - 1 - j; car[(size_t)((b * NCH + cj) * 2 + dir) * LW + c] = hc; hc = v[i].x * hc + v[i].y; }
;     }
	global_store_dword v7, v13, s[4:5]
	v_add_u32_e32 v7, v7, v10
	v_fma_f32 v13, v14, v13, v15
	global_store_dword v7, v13, s[4:5]
	v_add_u32_e32 v7, v7, v10
	v_fma_f32 v13, v16, v13, v17
	global_store_dword v7, v13, s[4:5]
	v_add_u32_e32 v7, v7, v10
	v_fma_f32 v13, v18, v13, v19
	global_store_dword v7, v13, s[4:5]
	v_add_u32_e32 v7, v7, v10
	v_fma_f32 v13, v20, v13, v21
	global_store_dword v7, v13, s[4:5]
	v_add_u32_e32 v7, v7, v10
	v_fma_f32 v13, v22, v13, v23
	global_store_dword v7, v13, s[4:5]
	v_add_u32_e32 v7, v7, v10
	v_fma_f32 v13, v24, v13, v25
	global_store_dword v7, v13, s[4:5]
	v_add_u32_e32 v7, v7, v10
	v_fma_f32 v13, v26, v13, v27
	global_store_dword v7, v13, s[4:5]
	v_add_u32_e32 v7, v7, v10
	v_fma_f32 v13, v28, v13, v29
	global_store_dword v7, v13, s[4:5]
	v_add_u32_e32 v7, v7, v10
	v_fma_f32 v13, v30, v13, v31
	global_store_dword v7, v13, s[4:5]
	v_add_u32_e32 v7, v7, v10
	v_fma_f32 v13, v32, v13, v33
	global_store_dword v7, v13, s[4:5]
	v_add_u32_e32 v7, v7, v10
	v_fma_f32 v13, v34, v13, v35
	global_store_dword v7, v13, s[4:5]
	v_add_u32_e32 v7, v7, v10
	v_fma_f32 v13, v36, v13, v37
	global_store_dword v7, v13, s[4:5]
	v_add_u32_e32 v7, v7, v10
	v_fma_f32 v13, v38, v13, v39
	global_store_dword v7, v13, s[4:5]
	v_add_u32_e32 v7, v7, v10
	v_fma_f32 v13, v40, v13, v41
	global_store_dword v7, v13, s[4:5]
	v_add_u32_e32 v7, v7, v10
	v_fma_f32 v13, v42, v13, v43
	global_store_dword v7, v13, s[4:5]
	v_add_u32_e32 v7, v7, v10
	v_fma_f32 v13, v44, v13, v45
	global_load_dwordx2 v[110:111], v6, s[74:75]
	v_add_u32_e32 v6, v6, v8
	global_load_dwordx2 v[112:113], v6, s[74:75]
	v_add_u32_e32 v6, v6, v8
	global_load_dwordx2 v[114:115], v6, s[74:75]
	v_add_u32_e32 v6, v6, v8
	global_load_dwordx2 v[116:117], v6, s[74:75]
	v_add_u32_e32 v6, v6, v8
	global_load_dwordx2 v[118:119], v6, s[74:75]
	v_add_u32_e32 v6, v6, v8
	global_load_dwordx2 v[120:121], v6, s[74:75]
	v_add_u32_e32 v6, v6, v8
	global_load_dwordx2 v[122:123], v6, s[74:75]
	v_add_u32_e32 v6, v6, v8
	global_load_dwordx2 v[124:125], v6, s[74:75]
	v_add_u32_e32 v6, v6, v8
	global_load_dwordx2 v[126:127], v6, s[74:75]
	v_add_u32_e32 v6, v6, v8
	global_load_dwordx2 v[128:129], v6, s[74:75]
	v_add_u32_e32 v6, v6, v8
	global_load_dwordx2 v[130:131], v6, s[74:75]
	v_add_u32_e32 v6, v6, v8
	global_load_dwordx2 v[132:133], v6, s[74:75]
	v_add_u32_e32 v6, v6, v8
	global_load_dwordx2 v[134:135], v6, s[74:75]
	v_add_u32_e32 v6, v6, v8
	global_load_dwordx2 v[136:137], v6, s[74:75]
	v_add_u32_e32 v6, v6, v8
	global_load_dwordx2 v[138:139], v6, s[74:75]
	v_add_u32_e32 v6, v6, v8
	global_load_dwordx2 v[140:141], v6, s[74:75]
	v_add_u32_e32 v6, v6, v8
	s_waitcnt vmcnt(48)
	global_store_dword v7, v13, s[4:5]
	v_add_u32_e32 v7, v7, v10
	v_fma_f32 v13, v46, v13, v47
	global_store_dword v7, v13, s[4:5]
	v_add_u32_e32 v7, v7, v10
	v_fma_f32 v13, v48, v13, v49
	global_store_dword v7, v13, s[4:5]
	v_add_u32_e32 v7, v7, v10
	v_fma_f32 v13, v50, v13, v51
	global_store_dword v7, v13, s[4:5]
	v_add_u32_e32 v7, v7, v10
	v_fma_f32 v13, v52, v13, v53
	global_store_dword v7, v13, s[4:5]
	v_add_u32_e32 v7, v7, v10
	v_fma_f32 v13, v54, v13, v55
	global_store_dword v7, v13, s[4:5]
	v_add_u32_e32 v7, v7, v10
	v_fma_f32 v13, v56, v13, v57
	global_store_dword v7, v13, s[4:5]
	v_add_u32_e32 v7, v7, v10
	v_fma_f32 v13, v58, v13, v59
	global_store_dword v7, v13, s[4:5]
	v_add_u32_e32 v7, v7, v10
	v_fma_f32 v13, v60, v13, v61
	global_store_dword v7, v13, s[4:5]
	v_add_u32_e32 v7, v7, v10
	v_fma_f32 v13, v62, v13, v63
	global_store_dword v7, v13, s[4:5]
	v_add_u32_e32 v7, v7, v10
	v_fma_f32 v13, v64, v13, v65
	global_store_dword v7, v13, s[4:5]
	v_add_u32_e32 v7, v7, v10
	v_fma_f32 v13, v66, v13, v67
	global_store_dword v7, v13, s[4:5]
	v_add_u32_e32 v7, v7, v10
	v_fma_f32 v13, v68, v13, v69
	global_store_dword v7, v13, s[4:5]
	v_add_u32_e32 v7, v7, v10
	v_fma_f32 v13, v70, v13, v71
	global_store_dword v7, v13, s[4:5]
	v_add_u32_e32 v7, v7, v10
	v_fma_f32 v13, v72, v13, v73
	global_store_dword v7, v13, s[4:5]
	v_add_u32_e32 v7, v7, v10
	v_fma_f32 v13, v74, v13, v75
	global_store_dword v7, v13, s[4:5]
	v_add_u32_e32 v7, v7, v10
	v_fma_f32 v13, v76, v13, v77
	global_load_dwordx2 v[14:15], v6, s[74:75]
	v_add_u32_e32 v6, v6, v8
	global_load_dwordx2 v[16:17], v6, s[74:75]
	v_add_u32_e32 v6, v6, v8
	global_load_dwordx2 v[18:19], v6, s[74:75]
	v_add_u32_e32 v6, v6, v8
	global_load_dwordx2 v[20:21], v6, s[74:75]
	v_add_u32_e32 v6, v6, v8
	global_load_dwordx2 v[22:23], v6, s[74:75]
	v_add_u32_e32 v6, v6, v8
	global_load_dwordx2 v[24:25], v6, s[74:75]
	v_add_u32_e32 v6, v6, v8
	global_load_dwordx2 v[26:27], v6, s[74:75]
	v_add_u32_e32 v6, v6, v8
	global_load_dwordx2 v[28:29], v6, s[74:75]
	v_add_u32_e32 v6, v6, v8
	global_load_dwordx2 v[30:31], v6, s[74:75]
	v_add_u32_e32 v6, v6, v8
	global_load_dwordx2 v[32:33], v6, s[74:75]
	v_add_u32_e32 v6, v6, v8
	global_load_dwordx2 v[34:35], v6, s[74:75]
	v_add_u32_e32 v6, v6, v8
	global_load_dwordx2 v[36:37], v6, s[74:75]
	v_add_u32_e32 v6, v6, v8
	global_load_dwordx2 v[38:39], v6, s[74:75]
	v_add_u32_e32 v6, v6, v8
	global_load_dwordx2 v[40:41], v6, s[74:75]
	v_add_u32_e32 v6, v6, v8
	global_load_dwordx2 v[42:43], v6, s[74:75]
	v_add_u32_e32 v6, v6, v8
	global_load_dwordx2 v[44:45], v6, s[74:75]
	v_add_u32_e32 v6, v6, v8
	s_waitcnt vmcnt(63)
; __device__ __forceinline__ void carry_phase(const Args& a, int bx) {
;     ...
;     for (int j0 = 0; j0 < NCH; j0 += 32) {
;         f32x2 v[32];
; #pragma unroll
;         for (int i = 0; i < 32; ++i) { const int j = j0 + i, cj = dir == 0 ? j : NCH - 1 - j; v[i] = tot[(size_t)((b * NCH + cj) * 2 + dir) * LW + c]; }
; #pragma unroll
;         for (int i = 0; i < 32; ++i) { const int j = j0 + i, cj = dir == 0 ? j : NCH - 1 - j; car[(size_t)((b * NCH + cj) * 2 + dir) * LW + c] = hc; hc = v[i].x * hc + v[i].y; }
;     }
	global_store_dword v7, v13, s[4:5]
	v_add_u32_e32 v7, v7, v10
	v_fma_f32 v13, v78, v13, v79
	global_store_dword v7, v13, s[4:5]
	v_add_u32_e32 v7, v7, v10
	v_fma_f32 v13, v80, v13, v81
	global_store_dword v7, v13, s[4:5]
	v_add_u32_e32 v7, v7, v10
	v_fma_f32 v13, v82, v13, v83
	global_store_dword v7, v13, s[4:5]
	v_add_u32_e32 v7, v7, v10
	v_fma_f32 v13, v84, v13, v85
	global_store_dword v7, v13, s[4:5]
	v_add_u32_e32 v7, v7, v10
	v_fma_f32 v13, v86, v13, v87
	global_store_dword v7, v13, s[4:5]
	v_add_u32_e32 v7, v7, v10
	v_fma_f32 v13, v88, v13, v89
	global_store_dword v7, v13, s[4:5]
	v_add_u32_e32 v7, v7, v10
	v_fma_f32 v13, v90, v13, v91
	global_store_dword v7, v13, s[4:5]
	v_add_u32_e32 v7, v7, v10
	v_fma_f32 v13, v92, v13, v93
	global_store_dword v7, v13, s[4:5]
	v_add_u32_e32 v7, v7, v10
	v_fma_f32 v13, v94, v13, v95
	global_store_dword v7, v13, s[4:5]
	v_add_u32_e32 v7, v7, v10
	v_fma_f32 v13, v96, v13, v97
	global_store_dword v7, v13, s[4:5]
	v_add_u32_e32 v7, v7, v10
	v_fma_f32 v13, v98, v13, v99
	global_store_dword v7, v13, s[4:5]
	v_add_u32_e32 v7, v7, v10
	v_fma_f32 v13, v100, v13, v101
	global_store_dword v7, v13, s[4:5]
	v_add_u32_e32 v7, v7, v10
	v_fma_f32 v13, v102, v13, v103
	global_store_dword v7, v13, s[4:5]
	v_add_u32_e32 v7, v7, v10
	v_fma_f32 v13, v104, v13, v105
	global_store_dword v7, v13, s[4:5]
	v_add_u32_e32 v7, v7, v10
	v_fma_f32 v13, v106, v13, v107
	global_store_dword v7, v13, s[4:5]
	v_add_u32_e32 v7, v7, v10
	v_fma_f32 v13, v108, v13, v109
	global_load_dwordx2 v[46:47], v6, s[74:75]
	v_add_u32_e32 v6, v6, v8
	global_load_dwordx2 v[48:49], v6, s[74:75]
	v_add_u32_e32 v6, v6, v8
	global_load_dwordx2 v[50:51], v6, s[74:75]
	v_add_u32_e32 v6, v6, v8
	global_load_dwordx2 v[52:53], v6, s[74:75]
	v_add_u32_e32 v6, v6, v8
	global_load_dwordx2 v[54:55], v6, s[74:75]
	v_add_u32_e32 v6, v6, v8
	global_load_dwordx2 v[56:57], v6, s[74:75]
	v_add_u32_e32 v6, v6, v8
	global_load_dwordx2 v[58:59], v6, s[74:75]
	v_add_u32_e32 v6, v6, v8
	global_load_dwordx2 v[60:61], v6, s[74:75]
	v_add_u32_e32 v6, v6, v8
	global_load_dwordx2 v[62:63], v6, s[74:75]
	v_add_u32_e32 v6, v6, v8
	global_load_dwordx2 v[64:65], v6, s[74:75]
	v_add_u32_e32 v6, v6, v8
	global_load_dwordx2 v[66:67], v6, s[74:75]
	v_add_u32_e32 v6, v6, v8
	global_load_dwordx2 v[68:69], v6, s[74:75]
	v_add_u32_e32 v6, v6, v8
	global_load_dwordx2 v[70:71], v6, s[74:75]
	v_add_u32_e32 v6, v6, v8
	global_load_dwordx2 v[72:73], v6, s[74:75]
	v_add_u32_e32 v6, v6, v8
	global_load_dwordx2 v[74:75], v6, s[74:75]
	v_add_u32_e32 v6, v6, v8
	global_load_dwordx2 v[76:77], v6, s[74:75]
	v_add_u32_e32 v6, v6, v8
	s_waitcnt vmcnt(63)
	global_store_dword v7, v13, s[4:5]
	v_add_u32_e32 v7, v7, v10
	v_fma_f32 v13, v110, v13, v111
	global_store_dword v7, v13, s[4:5]
	v_add_u32_e32 v7, v7, v10
	v_fma_f32 v13, v112, v13, v113
	global_store_dword v7, v13, s[4:5]
	v_add_u32_e32 v7, v7, v10
	v_fma_f32 v13, v114, v13, v115
	global_store_dword v7, v13, s[4:5]
	v_add_u32_e32 v7, v7, v10
	v_fma_f32 v13, v116, v13, v117
	global_store_dword v7, v13, s[4:5]
	v_add_u32_e32 v7, v7, v10
	v_fma_f32 v13, v118, v13, v119
	global_store_dword v7, v13, s[4:5]
	v_add_u32_e32 v7, v7, v10
	v_fma_f32 v13, v120, v13, v121
	global_store_dword v7, v13, s[4:5]
	v_add_u32_e32 v7, v7, v10
	v_fma_f32 v13, v122, v13, v123
	global_store_dword v7, v13, s[4:5]
	v_add_u32_e32 v7, v7, v10
	v_fma_f32 v13, v124, v13, v125
	global_store_dword v7, v13, s[4:5]
	v_add_u32_e32 v7, v7, v10
	v_fma_f32 v13, v126, v13, v127
	global_store_dword v7, v13, s[4:5]
	v_add_u32_e32 v7, v7, v10
	v_fma_f32 v13, v128, v13, v129
	global_store_dword v7, v13, s[4:5]
	v_add_u32_e32 v7, v7, v10
	v_fma_f32 v13, v130, v13, v131
	global_store_dword v7, v13, s[4:5]
	v_add_u32_e32 v7, v7, v10
	v_fma_f32 v13, v132, v13, v133
	global_store_dword v7, v13, s[4:5]
	v_add_u32_e32 v7, v7, v10
	v_fma_f32 v13, v134, v13, v135
	global_store_dword v7, v13, s[4:5]
	v_add_u32_e32 v7, v7, v10
	v_fma_f32 v13, v136, v13, v137
	global_store_dword v7, v13, s[4:5]
	v_add_u32_e32 v7, v7, v10
	v_fma_f32 v13, v138, v13, v139
	global_store_dword v7, v13, s[4:5]
	v_add_u32_e32 v7, v7, v10
	v_fma_f32 v13, v140, v13, v141
	global_load_dwordx2 v[78:79], v6, s[74:75]
	v_add_u32_e32 v6, v6, v8
	global_load_dwordx2 v[80:81], v6, s[74:75]
	v_add_u32_e32 v6, v6, v8
	global_load_dwordx2 v[82:83], v6, s[74:75]
	v_add_u32_e32 v6, v6, v8
	global_load_dwordx2 v[84:85], v6, s[74:75]
	v_add_u32_e32 v6, v6, v8
	global_load_dwordx2 v[86:87], v6, s[74:75]
	v_add_u32_e32 v6, v6, v8
	global_load_dwordx2 v[88:89], v6, s[74:75]
	v_add_u32_e32 v6, v6, v8
	global_load_dwordx2 v[90:91], v6, s[74:75]
	v_add_u32_e32 v6, v6, v8
	global_load_dwordx2 v[92:93], v6, s[74:75]
	v_add_u32_e32 v6, v6, v8
	global_load_dwordx2 v[94:95], v6, s[74:75]
	v_add_u32_e32 v6, v6, v8
	global_load_dwordx2 v[96:97], v6, s[74:75]
	v_add_u32_e32 v6, v6, v8
	global_load_dwordx2 v[98:99], v6, s[74:75]
	v_add_u32_e32 v6, v6, v8
	global_load_dwordx2 v[100:101], v6, s[74:75]
	v_add_u32_e32 v6, v6, v8
	global_load_dwordx2 v[102:103], v6, s[74:75]
	v_add_u32_e32 v6, v6, v8
	global_load_dwordx2 v[104:105], v6, s[74:75]
	v_add_u32_e32 v6, v6, v8
	global_load_dwordx2 v[106:107], v6, s[74:75]
	v_add_u32_e32 v6, v6, v8
	global_load_dwordx2 v[108:109], v6, s[74:75]
	v_add_u32_e32 v6, v6, v8
	s_waitcnt vmcnt(63)
; __device__ __forceinline__ void carry_phase(const Args& a, int bx) {
;     ...
;     for (int j0 = 0; j0 < NCH; j0 += 32) {
;         f32x2 v[32];
; #pragma unroll
;         for (int i = 0; i < 32; ++i) { const int j = j0 + i, cj = dir == 0 ? j : NCH - 1 - j; v[i] = tot[(size_t)((b * NCH + cj) * 2 + dir) * LW + c]; }
; #pragma unroll
;         for (int i = 0; i < 32; ++i) { const int j = j0 + i, cj = dir == 0 ? j : NCH - 1 - j; car[(size_t)((b * NCH + cj) * 2 + dir) * LW + c] = hc; hc = v[i].x * hc + v[i].y; }
;     }
	global_store_dword v7, v13, s[4:5]
	v_add_u32_e32 v7, v7, v10
	v_fma_f32 v13, v14, v13, v15
	global_store_dword v7, v13, s[4:5]
	v_add_u32_e32 v7, v7, v10
	v_fma_f32 v13, v16, v13, v17
	global_store_dword v7, v13, s[4:5]
	v_add_u32_e32 v7, v7, v10
	v_fma_f32 v13, v18, v13, v19
	global_store_dword v7, v13, s[4:5]
	v_add_u32_e32 v7, v7, v10
	v_fma_f32 v13, v20, v13, v21
	global_store_dword v7, v13, s[4:5]
	v_add_u32_e32 v7, v7, v10
	v_fma_f32 v13, v22, v13, v23
	global_store_dword v7, v13, s[4:5]
	v_add_u32_e32 v7, v7, v10
	v_fma_f32 v13, v24, v13, v25
	global_store_dword v7, v13, s[4:5]
	v_add_u32_e32 v7, v7, v10
	v_fma_f32 v13, v26, v13, v27
	global_store_dword v7, v13, s[4:5]
	v_add_u32_e32 v7, v7, v10
	v_fma_f32 v13, v28, v13, v29
	global_store_dword v7, v13, s[4:5]
	v_add_u32_e32 v7, v7, v10
	v_fma_f32 v13, v30, v13, v31
	global_store_dword v7, v13, s[4:5]
	v_add_u32_e32 v7, v7, v10
	v_fma_f32 v13, v32, v13, v33
	global_store_dword v7, v13, s[4:5]
	v_add_u32_e32 v7, v7, v10
	v_fma_f32 v13, v34, v13, v35
	global_store_dword v7, v13, s[4:5]
	v_add_u32_e32 v7, v7, v10
	v_fma_f32 v13, v36, v13, v37
	global_store_dword v7, v13, s[4:5]
	v_add_u32_e32 v7, v7, v10
	v_fma_f32 v13, v38, v13, v39
	global_store_dword v7, v13, s[4:5]
	v_add_u32_e32 v7, v7, v10
	v_fma_f32 v13, v40, v13, v41
	global_store_dword v7, v13, s[4:5]
	v_add_u32_e32 v7, v7, v10
	v_fma_f32 v13, v42, v13, v43
	global_store_dword v7, v13, s[4:5]
	v_add_u32_e32 v7, v7, v10
	v_fma_f32 v13, v44, v13, v45
	global_load_dwordx2 v[110:111], v6, s[74:75]
	v_add_u32_e32 v6, v6, v8
	global_load_dwordx2 v[112:113], v6, s[74:75]
	v_add_u32_e32 v6, v6, v8
	global_load_dwordx2 v[114:115], v6, s[74:75]
	v_add_u32_e32 v6, v6, v8
	global_load_dwordx2 v[116:117], v6, s[74:75]
	v_add_u32_e32 v6, v6, v8
	global_load_dwordx2 v[118:119], v6, s[74:75]
	v_add_u32_e32 v6, v6, v8
	global_load_dwordx2 v[120:121], v6, s[74:75]
	v_add_u32_e32 v6, v6, v8
	global_load_dwordx2 v[122:123], v6, s[74:75]
	v_add_u32_e32 v6, v6, v8
	global_load_dwordx2 v[124:125], v6, s[74:75]
	v_add_u32_e32 v6, v6, v8
	global_load_dwordx2 v[126:127], v6, s[74:75]
	v_add_u32_e32 v6, v6, v8
	global_load_dwordx2 v[128:129], v6, s[74:75]
	v_add_u32_e32 v6, v6, v8
	global_load_dwordx2 v[130:131], v6, s[74:75]
	v_add_u32_e32 v6, v6, v8
	global_load_dwordx2 v[132:133], v6, s[74:75]
	v_add_u32_e32 v6, v6, v8
	global_load_dwordx2 v[134:135], v6, s[74:75]
	v_add_u32_e32 v6, v6, v8
	global_load_dwordx2 v[136:137], v6, s[74:75]
	v_add_u32_e32 v6, v6, v8
	global_load_dwordx2 v[138:139], v6, s[74:75]
	v_add_u32_e32 v6, v6, v8
	global_load_dwordx2 v[140:141], v6, s[74:75]
	v_add_u32_e32 v6, v6, v8
	s_waitcnt vmcnt(63)
	global_store_dword v7, v13, s[4:5]
	v_add_u32_e32 v7, v7, v10
	v_fma_f32 v13, v46, v13, v47
	global_store_dword v7, v13, s[4:5]
	v_add_u32_e32 v7, v7, v10
	v_fma_f32 v13, v48, v13, v49
	global_store_dword v7, v13, s[4:5]
	v_add_u32_e32 v7, v7, v10
	v_fma_f32 v13, v50, v13, v51
	global_store_dword v7, v13, s[4:5]
	v_add_u32_e32 v7, v7, v10
	v_fma_f32 v13, v52, v13, v53
	global_store_dword v7, v13, s[4:5]
	v_add_u32_e32 v7, v7, v10
	v_fma_f32 v13, v54, v13, v55
	global_store_dword v7, v13, s[4:5]
	v_add_u32_e32 v7, v7, v10
	v_fma_f32 v13, v56, v13, v57
	global_store_dword v7, v13, s[4:5]
	v_add_u32_e32 v7, v7, v10
	v_fma_f32 v13, v58, v13, v59
	global_store_dword v7, v13, s[4:5]
	v_add_u32_e32 v7, v7, v10
	v_fma_f32 v13, v60, v13, v61
	global_store_dword v7, v13, s[4:5]
	v_add_u32_e32 v7, v7, v10
	v_fma_f32 v13, v62, v13, v63
	global_store_dword v7, v13, s[4:5]
	v_add_u32_e32 v7, v7, v10
	v_fma_f32 v13, v64, v13, v65
	global_store_dword v7, v13, s[4:5]
	v_add_u32_e32 v7, v7, v10
	v_fma_f32 v13, v66, v13, v67
	global_store_dword v7, v13, s[4:5]
	v_add_u32_e32 v7, v7, v10
	v_fma_f32 v13, v68, v13, v69
	global_store_dword v7, v13, s[4:5]
	v_add_u32_e32 v7, v7, v10
	v_fma_f32 v13, v70, v13, v71
	global_store_dword v7, v13, s[4:5]
	v_add_u32_e32 v7, v7, v10
	v_fma_f32 v13, v72, v13, v73
	global_store_dword v7, v13, s[4:5]
	v_add_u32_e32 v7, v7, v10
	v_fma_f32 v13, v74, v13, v75
	global_store_dword v7, v13, s[4:5]
	v_add_u32_e32 v7, v7, v10
	v_fma_f32 v13, v76, v13, v77
	s_waitcnt vmcnt(48)
; __device__ __forceinline__ void carry_phase(const Args& a, int bx) {
;     ...
;     for (int j0 = 0; j0 < NCH; j0 += 32) {
;         f32x2 v[32];
; #pragma unroll
;         for (int i = 0; i < 32; ++i) { const int j = j0 + i, cj = dir == 0 ? j : NCH - 1 - j; v[i] = tot[(size_t)((b * NCH + cj) * 2 + dir) * LW + c]; }
; #pragma unroll
;         for (int i = 0; i < 32; ++i) { const int j = j0 + i, cj = dir == 0 ? j : NCH - 1 - j; car[(size_t)((b * NCH + cj) * 2 + dir) * LW + c] = hc; hc = v[i].x * hc + v[i].y; }
;     }
	global_store_dword v7, v13, s[4:5]
	v_add_u32_e32 v7, v7, v10
	v_fma_f32 v13, v78, v13, v79
	global_store_dword v7, v13, s[4:5]
	v_add_u32_e32 v7, v7, v10
	v_fma_f32 v13, v80, v13, v81
	global_store_dword v7, v13, s[4:5]
	v_add_u32_e32 v7, v7, v10
	v_fma_f32 v13, v82, v13, v83
	global_store_dword v7, v13, s[4:5]
	v_add_u32_e32 v7, v7, v10
	v_fma_f32 v13, v84, v13, v85
	global_store_dword v7, v13, s[4:5]
	v_add_u32_e32 v7, v7, v10
	v_fma_f32 v13, v86, v13, v87
	global_store_dword v7, v13, s[4:5]
	v_add_u32_e32 v7, v7, v10
	v_fma_f32 v13, v88, v13, v89
	global_store_dword v7, v13, s[4:5]
	v_add_u32_e32 v7, v7, v10
	v_fma_f32 v13, v90, v13, v91
	global_store_dword v7, v13, s[4:5]
	v_add_u32_e32 v7, v7, v10
	v_fma_f32 v13, v92, v13, v93
	global_store_dword v7, v13, s[4:5]
	v_add_u32_e32 v7, v7, v10
	v_fma_f32 v13, v94, v13, v95
	global_store_dword v7, v13, s[4:5]
	v_add_u32_e32 v7, v7, v10
	v_fma_f32 v13, v96, v13, v97
	global_store_dword v7, v13, s[4:5]
	v_add_u32_e32 v7, v7, v10
	v_fma_f32 v13, v98, v13, v99
	global_store_dword v7, v13, s[4:5]
	v_add_u32_e32 v7, v7, v10
	v_fma_f32 v13, v100, v13, v101
	global_store_dword v7, v13, s[4:5]
	v_add_u32_e32 v7, v7, v10
	v_fma_f32 v13, v102, v13, v103
	global_store_dword v7, v13, s[4:5]
	v_add_u32_e32 v7, v7, v10
	v_fma_f32 v13, v104, v13, v105
	global_store_dword v7, v13, s[4:5]
	v_add_u32_e32 v7, v7, v10
	v_fma_f32 v13, v106, v13, v107
	global_store_dword v7, v13, s[4:5]
	v_add_u32_e32 v7, v7, v10
	v_fma_f32 v13, v108, v13, v109
	s_waitcnt vmcnt(32)
	global_store_dword v7, v13, s[4:5]
	v_add_u32_e32 v7, v7, v10
	v_fma_f32 v13, v110, v13, v111
	global_store_dword v7, v13, s[4:5]
	v_add_u32_e32 v7, v7, v10
	v_fma_f32 v13, v112, v13, v113
	global_store_dword v7, v13, s[4:5]
	v_add_u32_e32 v7, v7, v10
	v_fma_f32 v13, v114, v13, v115
	global_store_dword v7, v13, s[4:5]
	v_add_u32_e32 v7, v7, v10
	v_fma_f32 v13, v116, v13, v117
	global_store_dword v7, v13, s[4:5]
	v_add_u32_e32 v7, v7, v10
	v_fma_f32 v13, v118, v13, v119
	global_store_dword v7, v13, s[4:5]
	v_add_u32_e32 v7, v7, v10
	v_fma_f32 v13, v120, v13, v121
	global_store_dword v7, v13, s[4:5]
	v_add_u32_e32 v7, v7, v10
	v_fma_f32 v13, v122, v13, v123
	global_store_dword v7, v13, s[4:5]
	v_add_u32_e32 v7, v7, v10
	v_fma_f32 v13, v124, v13, v125
	global_store_dword v7, v13, s[4:5]
	v_add_u32_e32 v7, v7, v10
	v_fma_f32 v13, v126, v13, v127
	global_store_dword v7, v13, s[4:5]
	v_add_u32_e32 v7, v7, v10
	v_fma_f32 v13, v128, v13, v129
	global_store_dword v7, v13, s[4:5]
	v_add_u32_e32 v7, v7, v10
	v_fma_f32 v13, v130, v13, v131
	global_store_dword v7, v13, s[4:5]
	v_add_u32_e32 v7, v7, v10
	v_fma_f32 v13, v132, v13, v133
	global_store_dword v7, v13, s[4:5]
	v_add_u32_e32 v7, v7, v10
	v_fma_f32 v13, v134, v13, v135
	global_store_dword v7, v13, s[4:5]
	v_add_u32_e32 v7, v7, v10
	v_fma_f32 v13, v136, v13, v137
	global_store_dword v7, v13, s[4:5]
	v_add_u32_e32 v7, v7, v10
	v_fma_f32 v13, v138, v13, v139
	global_store_dword v7, v13, s[4:5]
	v_add_u32_e32 v7, v7, v10
	v_fma_f32 v13, v140, v13, v141
